# v76 plus gla_g3 unit load de-serialisation: q/k/v/state loads issued with the decay loads, epilogue gate and norm-gain loads issued together
# baseline (speedup 1.0000x reference)
.LBB0_89:
	s_or_b64 exec, exec, s[28:29]
	v_lshlrev_b32_e32 v18, 7, v56
	v_sub_u32_e32 v18, v57, v18
	s_waitcnt lgkmcnt(0)
	s_barrier
	ds_read_b128 v[18:21], v18 offset:57344
	s_mov_b32 s3, 0x800000
	v_ashrrev_i32_e32 v51, 31, v50
	v_mov_b64_e32 v[22:23], s[84:85]
	s_lshl_b32 s94, s37, 1
	s_waitcnt lgkmcnt(0)
	v_add_f32_e32 v18, v18, v19
	v_add_f32_e32 v18, v20, v18
	v_add_f32_e32 v18, v21, v18
	v_fmamk_f32 v18, v18, 0x3c000000, v184
	v_cmp_gt_f32_e32 vcc, s3, v18
	v_mul_f32_e32 v19, 0x4b800000, v18
	v_lshl_add_u64 v[20:21], s[38:39], 0, v[50:51]
	v_cndmask_b32_e32 v18, v18, v19, vcc
	v_rsq_f32_e32 v18, v18
	v_or_b32_e32 v20, v20, v0
	v_mad_u64_u32 v[22:23], s[28:29], v20, s64, v[22:23]
	v_mov_b32_e32 v0, v23
	v_mul_f32_e32 v19, 0x45800000, v18
	v_mad_u64_u32 v[24:25], s[28:29], v21, s64, v[0:1]
	v_cndmask_b32_e32 v18, v18, v19, vcc
	v_or_b32_e32 v19, v53, v54
	v_mov_b32_e32 v23, v24
	v_lshl_add_u64 v[22:23], v[22:23], 0, s[94:95]
	v_lshlrev_b32_e32 v0, 1, v19
	v_lshl_add_u64 v[22:23], v[22:23], 0, v[0:1]
	global_load_dwordx2 v[28:29], v[22:23], off offset:2048
	v_lshlrev_b32_e32 v19, 2, v19
	global_load_dwordx4 v[24:27], v19, s[0:1]
	global_load_dwordx2 v[100:101], v[22:23], off offset:2064
	global_load_dwordx4 v[104:107], v19, s[0:1] offset:32
	global_load_dwordx2 v[102:103], v[22:23], off offset:2080
	global_load_dwordx4 v[108:111], v19, s[0:1] offset:64
	global_load_dwordx2 v[112:113], v[22:23], off offset:2096
	global_load_dwordx4 v[116:119], v19, s[0:1] offset:96
	v_pk_mul_f32 v[2:3], v[2:3], v[18:19] op_sel_hi:[1,0]
	v_pk_mul_f32 v[4:5], v[4:5], v[18:19] op_sel_hi:[1,0]
	v_lshlrev_b64 v[20:21], 11, v[20:21]
	v_lshl_add_u64 v[20:21], s[90:91], 0, v[20:21]
	v_lshl_add_u64 v[20:21], v[20:21], 0, s[94:95]
	v_lshl_add_u64 v[20:21], v[20:21], 0, v[0:1]
	v_pk_mul_f32 v[6:7], v[6:7], v[18:19] op_sel_hi:[1,0]
	v_pk_mul_f32 v[8:9], v[8:9], v[18:19] op_sel_hi:[1,0]
	v_pk_mul_f32 v[10:11], v[10:11], v[18:19] op_sel_hi:[1,0]
	v_readlane_b32 s28, v249, 3
	v_readlane_b32 s29, v249, 4
	s_waitcnt vmcnt(7)
	v_lshlrev_b32_e32 v30, 16, v28
	v_and_b32_e32 v31, 0xffff0000, v28
	v_mul_f32_e32 v28, 0xbfb8aa3b, v30
	s_waitcnt vmcnt(6)
	v_pk_mul_f32 v[2:3], v[24:25], v[2:3]
	v_mul_f32_e32 v24, 0xbfb8aa3b, v31
	v_exp_f32_e32 v28, v28
	v_exp_f32_e32 v24, v24
	v_pk_mul_f32 v[4:5], v[26:27], v[4:5]
	v_add_f32_e32 v28, 1.0, v28
	v_add_f32_e32 v24, 1.0, v24
	v_rcp_f32_e32 v32, v28
	v_rcp_f32_e32 v33, v24
	s_nop 0
	v_pk_mul_f32 v[24:25], v[32:33], v[30:31]
	s_nop 0
	v_pk_mul_f32 v[2:3], v[24:25], v[2:3]
	v_lshlrev_b32_e32 v24, 16, v29
	v_and_b32_e32 v25, 0xffff0000, v29
	v_mul_f32_e32 v28, 0xbfb8aa3b, v24
	v_mul_f32_e32 v26, 0xbfb8aa3b, v25
	v_exp_f32_e32 v28, v28
	v_exp_f32_e32 v26, v26
	v_cvt_pk_bf16_f32 v2, v2, v3
	v_add_f32_e32 v28, 1.0, v28
	v_add_f32_e32 v26, 1.0, v26
	v_rcp_f32_e32 v28, v28
	v_rcp_f32_e32 v29, v26
	s_nop 0
	v_pk_mul_f32 v[24:25], v[28:29], v[24:25]
	s_nop 0
	v_pk_mul_f32 v[4:5], v[24:25], v[4:5]
	s_nop 0
	v_cvt_pk_bf16_f32 v3, v4, v5
	global_store_dwordx2 v[20:21], v[2:3], off
	s_waitcnt vmcnt(5)
	v_mov_b32_e32 v24, v100
	v_mov_b32_e32 v25, v101
	v_mov_b32_e32 v2, v104
	v_mov_b32_e32 v3, v105
	v_mov_b32_e32 v4, v106
	v_mov_b32_e32 v5, v107
	v_lshlrev_b32_e32 v26, 16, v24
	v_mul_f32_e32 v0, 0xbfb8aa3b, v26
	v_exp_f32_e32 v0, v0
	v_and_b32_e32 v27, 0xffff0000, v24
	v_pk_mul_f32 v[2:3], v[2:3], v[6:7]
	v_pk_mul_f32 v[4:5], v[4:5], v[8:9]
	v_add_f32_e32 v0, 1.0, v0
	v_rcp_f32_e32 v28, v0
	v_mul_f32_e32 v0, 0xbfb8aa3b, v27
	v_exp_f32_e32 v0, v0
	s_nop 0
	v_add_f32_e32 v0, 1.0, v0
	v_rcp_f32_e32 v29, v0
	s_nop 0
	v_pk_mul_f32 v[6:7], v[28:29], v[26:27]
	s_nop 0
	v_pk_mul_f32 v[2:3], v[6:7], v[2:3]
	v_lshlrev_b32_e32 v6, 16, v25
	v_mul_f32_e32 v0, 0xbfb8aa3b, v6
	v_exp_f32_e32 v0, v0
	v_and_b32_e32 v7, 0xffff0000, v25
	v_cvt_pk_bf16_f32 v2, v2, v3
	v_add_f32_e32 v0, 1.0, v0
	v_rcp_f32_e32 v24, v0
	v_mul_f32_e32 v0, 0xbfb8aa3b, v7
	v_exp_f32_e32 v0, v0
	s_nop 0
	v_add_f32_e32 v0, 1.0, v0
	v_rcp_f32_e32 v25, v0
	s_nop 0
	v_pk_mul_f32 v[6:7], v[24:25], v[6:7]
	s_nop 0
	v_pk_mul_f32 v[4:5], v[6:7], v[4:5]
	s_nop 0
	v_cvt_pk_bf16_f32 v3, v4, v5
	global_store_dwordx2 v[20:21], v[2:3], off offset:16
	s_waitcnt vmcnt(4)
	v_mov_b32_e32 v6, v102
	v_mov_b32_e32 v7, v103
	v_mov_b32_e32 v2, v108
	v_mov_b32_e32 v3, v109
	v_mov_b32_e32 v4, v110
	v_mov_b32_e32 v5, v111
	v_lshlrev_b32_e32 v8, 16, v6
	v_mul_f32_e32 v0, 0xbfb8aa3b, v8
	v_exp_f32_e32 v0, v0
	v_and_b32_e32 v9, 0xffff0000, v6
	v_lshlrev_b32_e32 v6, 16, v7
	v_pk_mul_f32 v[2:3], v[2:3], v[10:11]
	v_add_f32_e32 v0, 1.0, v0
	v_rcp_f32_e32 v24, v0
	v_mul_f32_e32 v0, 0xbfb8aa3b, v9
	v_exp_f32_e32 v0, v0
	v_and_b32_e32 v7, 0xffff0000, v7
	v_pk_mul_f32 v[10:11], v[12:13], v[18:19] op_sel_hi:[1,0]
	v_pk_mul_f32 v[12:13], v[14:15], v[18:19] op_sel_hi:[1,0]
	v_add_f32_e32 v0, 1.0, v0
	v_rcp_f32_e32 v25, v0
	v_mul_f32_e32 v0, 0xbfb8aa3b, v6
	v_exp_f32_e32 v0, v0
	v_pk_mul_f32 v[4:5], v[4:5], v[10:11]
	v_pk_mul_f32 v[8:9], v[24:25], v[8:9]
	v_add_f32_e32 v0, 1.0, v0
	v_pk_mul_f32 v[2:3], v[2:3], v[8:9]
	v_rcp_f32_e32 v8, v0
	v_mul_f32_e32 v0, 0xbfb8aa3b, v7
	v_exp_f32_e32 v0, v0
	v_cvt_pk_bf16_f32 v2, v2, v3
	v_add_f32_e32 v0, 1.0, v0
	v_rcp_f32_e32 v9, v0
	s_nop 0
	v_pk_mul_f32 v[6:7], v[8:9], v[6:7]
	s_nop 0
	v_pk_mul_f32 v[4:5], v[4:5], v[6:7]
	s_nop 0
	v_cvt_pk_bf16_f32 v3, v4, v5
	global_store_dwordx2 v[20:21], v[2:3], off offset:32
	s_waitcnt vmcnt(3)
	v_mov_b32_e32 v6, v112
	v_mov_b32_e32 v7, v113
	v_mov_b32_e32 v2, v116
	v_mov_b32_e32 v3, v117
	v_mov_b32_e32 v4, v118
	v_mov_b32_e32 v5, v119
	v_lshlrev_b32_e32 v8, 16, v6
	v_mul_f32_e32 v0, 0xbfb8aa3b, v8
	v_exp_f32_e32 v0, v0
	v_and_b32_e32 v9, 0xffff0000, v6
	v_lshlrev_b32_e32 v6, 16, v7
	v_pk_mul_f32 v[2:3], v[2:3], v[12:13]
	v_add_f32_e32 v0, 1.0, v0
	v_rcp_f32_e32 v10, v0
	v_mul_f32_e32 v0, 0xbfb8aa3b, v9
	v_exp_f32_e32 v0, v0
	v_and_b32_e32 v7, 0xffff0000, v7
	v_add_f32_e32 v0, 1.0, v0
	v_rcp_f32_e32 v11, v0
	v_mul_f32_e32 v0, 0xbfb8aa3b, v6
	v_exp_f32_e32 v0, v0
	v_pk_mul_f32 v[8:9], v[10:11], v[8:9]
	s_nop 0
	v_pk_mul_f32 v[2:3], v[2:3], v[8:9]
	v_add_f32_e32 v0, 1.0, v0
	v_rcp_f32_e32 v8, v0
	v_mul_f32_e32 v0, 0xbfb8aa3b, v7
	v_exp_f32_e32 v0, v0
	v_pk_mul_f32 v[10:11], v[16:17], v[18:19] op_sel_hi:[1,0]
	v_cvt_pk_bf16_f32 v2, v2, v3
	v_pk_mul_f32 v[4:5], v[4:5], v[10:11]
	v_add_f32_e32 v0, 1.0, v0
	v_rcp_f32_e32 v9, v0
	s_nop 0
	v_pk_mul_f32 v[6:7], v[8:9], v[6:7]
	s_nop 0
	v_pk_mul_f32 v[4:5], v[4:5], v[6:7]
	s_nop 0
	v_cvt_pk_bf16_f32 v3, v4, v5
	global_store_dwordx2 v[20:21], v[2:3], off offset:48
	s_load_dword s3, s[28:29], 0x10
	s_waitcnt lgkmcnt(0)
	s_lshr_b32 s3, s3, 16
	s_cmp_lg_u32 s3, 0
	s_cselect_b64 s[28:29], -1, 0
	s_cmp_lg_u64 s[28:29], 0
	s_addc_u32 s2, s2, s30
	s_cmpk_gt_i32 s2, 0x7ff
	s_cbranch_scc1 .LBB0_87
.LBB0_90:
	s_ashr_i32 s28, s2, 8
	s_ashr_i32 s29, s28, 31
	v_mov_b32_e32 v52, v180
	s_lshl_b64 s[38:39], s[28:29], 12
	s_lshl_b32 s28, s2, 6
	v_mov_b32_e32 v0, v180
	s_bfe_u32 s3, s2, 0x20006
	s_and_b32 s28, s28, 0xfc0
	s_barrier
	s_or_b32 s38, s38, s28
	v_ashrrev_i32_e32 v36, 6, v0
	s_waitcnt lgkmcnt(0)
	v_lshlrev_b32_e32 v2, 3, v36
	s_lshl_b32 s94, s3, 8
	v_readlane_b32 s28, v252, 51
	v_ashrrev_i32_e32 v3, 31, v2
	v_readlane_b32 s29, v252, 52
	s_add_u32 s28, s28, s94
	v_lshlrev_b32_e32 v10, 2, v0
	v_lshl_add_u64 v[2:3], s[38:39], 0, v[2:3]
	s_addc_u32 s29, s29, 0
	v_and_b32_e32 v0, 0xfc, v10
	v_lshl_add_u64 v[4:5], s[28:29], 0, v[0:1]
	v_lshlrev_b64 v[2:3], 10, v[2:3]
	v_lshl_add_u64 v[2:3], v[4:5], 0, v[2:3]
	v_add_co_u32_e32 v4, vcc, s31, v2
	v_ashrrev_i32_e32 v12, 6, v52
	s_nop 0
	v_addc_co_u32_e32 v5, vcc, 0, v3, vcc
	global_load_dword v13, v[2:3], off
	global_load_dword v11, v[2:3], off offset:1024
	global_load_dword v30, v[2:3], off offset:2048
	global_load_dword v31, v[2:3], off offset:3072
	global_load_dword v32, v[4:5], off
	global_load_dword v33, v[4:5], off offset:1024
	global_load_dword v34, v[4:5], off offset:2048
	global_load_dword v35, v[4:5], off offset:3072
	v_mov_b32_e32 v101, 0
	v_mov_b32_e32 v158, v180
	v_ashrrev_i32_e32 v112, 6, v158
	v_lshlrev_b32_e32 v102, 3, v112
	v_or_b32_e32 v104, 2, v102
	v_or_b32_e32 v106, 3, v102
	v_or_b32_e32 v108, 4, v102
	s_lshl_b32 s98, s3, 7
	v_and_b32_e32 v157, 63, v158
	v_ashrrev_i32_e32 v105, 31, v104
	v_ashrrev_i32_e32 v107, 31, v106
	v_ashrrev_i32_e32 v109, 31, v108
	s_add_u32 s100, s84, s98
	v_ashrrev_i32_e32 v103, 31, v102
	v_or_b32_e32 v114, 1, v102
	v_lshl_add_u64 v[124:125], s[38:39], 0, v[104:105]
	v_lshl_add_u64 v[126:127], s[38:39], 0, v[106:107]
	v_lshl_add_u64 v[128:129], s[38:39], 0, v[108:109]
	s_addc_u32 s101, s85, 0
	v_or_b32_e32 v116, 5, v102
	v_or_b32_e32 v118, 6, v102
	v_or_b32_e32 v120, 7, v102
	v_lshl_add_u64 v[102:103], s[38:39], 0, v[102:103]
	v_ashrrev_i32_e32 v115, 31, v114
	v_lshl_add_u64 v[122:123], s[38:39], 0, v[114:115]
	v_ashrrev_i32_e32 v117, 31, v116
	v_ashrrev_i32_e32 v119, 31, v118
	v_ashrrev_i32_e32 v121, 31, v120
	v_lshl_add_u64 v[116:117], s[38:39], 0, v[116:117]
	v_lshl_add_u64 v[118:119], s[38:39], 0, v[118:119]
	v_lshl_add_u64 v[120:121], s[38:39], 0, v[120:121]
	v_lshlrev_b32_e32 v100, 1, v157
	v_lshl_add_u64 v[136:137], s[100:101], 0, v[100:101]
	v_mad_u64_u32 v[138:139], s[100:101], v102, s64, v[136:137]
	v_mad_u64_u32 v[140:141], s[100:101], v122, s64, v[136:137]
	v_mad_i32_i24 v139, v103, s64, v139
	v_mad_i32_i24 v141, v123, s64, v141
	global_load_ushort v88, v[138:139], off
	global_load_ushort v89, v[138:139], off offset:512
	global_load_ushort v90, v[140:141], off
	global_load_ushort v91, v[140:141], off offset:512
	v_mad_u64_u32 v[114:115], s[100:101], v124, s64, v[136:137]
	v_mad_i32_i24 v115, v125, s64, v115
	global_load_ushort v92, v[114:115], off
	global_load_ushort v93, v[114:115], off offset:512
	v_mad_u64_u32 v[122:123], s[100:101], v126, s64, v[136:137]
	v_mad_u64_u32 v[138:139], s[100:101], v128, s64, v[136:137]
	v_mad_u64_u32 v[124:125], s[100:101], v116, s64, v[136:137]
	v_mad_u64_u32 v[140:141], s[100:101], v118, s64, v[136:137]
	v_mad_u64_u32 v[136:137], s[100:101], v120, s64, v[136:137]
	v_mad_i32_i24 v123, v127, s64, v123
	v_mad_i32_i24 v139, v129, s64, v139
	v_mad_i32_i24 v125, v117, s64, v125
	v_mad_i32_i24 v141, v119, s64, v141
	v_mad_i32_i24 v137, v121, s64, v137
	global_load_ushort v94, v[122:123], off
	global_load_ushort v95, v[122:123], off offset:512
	global_load_ushort v96, v[138:139], off
	global_load_ushort v97, v[138:139], off offset:512
	global_load_ushort v98, v[124:125], off
	global_load_ushort v99, v[124:125], off offset:512
	global_load_ushort v172, v[140:141], off
	global_load_ushort v173, v[140:141], off offset:512
	global_load_ushort v174, v[136:137], off
	global_load_ushort v175, v[136:137], off offset:512
	v_mov_b32_e32 v100, v180
	v_mov_b64_e32 v[104:105], s[84:85]
	v_ashrrev_i32_e32 v136, 7, v100
	v_lshlrev_b32_e32 v102, 4, v136
	v_ashrrev_i32_e32 v103, 31, v102
	v_lshl_add_u64 v[102:103], s[38:39], 0, v[102:103]
	v_mad_u64_u32 v[104:105], s[100:101], v102, s64, v[104:105]
	v_and_b32_e32 v113, 0x7f, v100
	v_mad_i32_i24 v105, v103, s64, v105
	v_lshl_add_u64 v[102:103], v[104:105], 0, s[94:95]
	v_lshlrev_b32_e32 v100, 1, v113
	v_lshl_add_u64 v[102:103], v[102:103], 0, v[100:101]
	v_add_co_u32_e32 v104, vcc, s31, v102
	s_nop 1
	v_ashrrev_i32_e32 v145, 2, v158
	v_addc_co_u32_e32 v105, vcc, 0, v103, vcc
	v_add_co_u32_e32 v106, vcc, 0x2000, v102
	s_nop 1
	v_addc_co_u32_e32 v107, vcc, 0, v103, vcc
	v_add_co_u32_e32 v108, vcc, 0x4000, v102
	s_nop 1
	v_addc_co_u32_e32 v109, vcc, 0, v103, vcc
	v_add_co_u32_e32 v110, vcc, 0x5000, v102
	s_nop 1
	v_addc_co_u32_e32 v111, vcc, 0, v103, vcc
	v_add_co_u32_e32 v114, vcc, 0x6000, v102
	s_nop 1
	v_addc_co_u32_e32 v115, vcc, 0, v103, vcc
	v_add_co_u32_e32 v116, vcc, 0x7000, v102
	s_nop 1
	v_addc_co_u32_e32 v117, vcc, 0, v103, vcc
	v_add_co_u32_e32 v118, vcc, 0x9000, v102
	s_nop 1
	v_addc_co_u32_e32 v119, vcc, 0, v103, vcc
	global_load_ushort v176, v[102:103], off offset:1024
	global_load_ushort v177, v[104:105], off offset:2048
	global_load_ushort v178, v[106:107], off offset:3072
	global_load_ushort v179, v[108:109], off
	global_load_ushort v195, v[110:111], off offset:1024
	global_load_ushort v196, v[114:115], off offset:2048
	global_load_ushort v197, v[116:117], off offset:3072
	global_load_ushort v198, v[118:119], off
	v_add_co_u32_e32 v104, vcc, 0xa000, v102
	s_nop 1
	v_addc_co_u32_e32 v105, vcc, 0, v103, vcc
	v_add_co_u32_e32 v106, vcc, 0xb000, v102
	s_nop 1
	v_addc_co_u32_e32 v107, vcc, 0, v103, vcc
	v_add_co_u32_e32 v108, vcc, 0xc000, v102
	s_nop 1
	v_addc_co_u32_e32 v109, vcc, 0, v103, vcc
	v_add_co_u32_e32 v110, vcc, 0xe000, v102
	s_nop 1
	v_addc_co_u32_e32 v111, vcc, 0, v103, vcc
	v_add_co_u32_e32 v114, vcc, 0xf000, v102
	s_nop 1
	v_addc_co_u32_e32 v115, vcc, 0, v103, vcc
	v_add_co_u32_e32 v116, vcc, 0x10000, v102
	s_nop 1
	v_addc_co_u32_e32 v117, vcc, 0, v103, vcc
	v_add_co_u32_e32 v118, vcc, 0x11000, v102
	s_nop 1
	v_addc_co_u32_e32 v119, vcc, 0, v103, vcc
	v_add_co_u32_e32 v102, vcc, 0x13000, v102
	s_nop 1
	s_ashr_i32 s99, s2, 31
	s_mov_b32 s98, s2
	s_lshl_b64 s[100:101], s[98:99], 15
	v_addc_co_u32_e32 v103, vcc, 0, v103, vcc
	global_load_ushort v199, v[104:105], off offset:1024
	global_load_ushort v200, v[106:107], off offset:2048
	global_load_ushort v201, v[108:109], off offset:3072
	global_load_ushort v202, v[110:111], off
	global_load_ushort v203, v[114:115], off offset:1024
	global_load_ushort v204, v[116:117], off offset:2048
	global_load_ushort v205, v[118:119], off offset:3072
	global_load_ushort v206, v[102:103], off
	s_add_u32 s100, s82, s100
	v_lshlrev_b32_e32 v102, 6, v145
	v_and_b32_e32 v146, 3, v158
	s_addc_u32 s101, s83, s101
	v_ashrrev_i32_e32 v103, 31, v102
	v_lshl_add_u64 v[102:103], v[102:103], 2, s[100:101]
	v_lshlrev_b32_e32 v100, 6, v146
	v_lshl_add_u64 v[110:111], v[102:103], 0, v[100:101]
	global_load_dwordx4 v[66:69], v[110:111], off
	global_load_dwordx4 v[70:73], v[110:111], off offset:16
	global_load_dwordx4 v[74:77], v[110:111], off offset:32
	global_load_dwordx4 v[78:81], v[110:111], off offset:48
	v_lshlrev_b32_e32 v2, 3, v12
	s_movk_i32 s28, 0x480
	v_or_b32_e32 v4, 2, v2
	v_or_b32_e32 v6, 3, v2
	v_or_b32_e32 v8, 4, v2
	s_lshl_b32 s37, s3, 7
	v_and_b32_e32 v51, 63, v52
	v_mul_lo_u32 v37, v12, s28
	v_ashrrev_i32_e32 v5, 31, v4
	v_ashrrev_i32_e32 v7, 31, v6
	v_ashrrev_i32_e32 v9, 31, v8
	s_add_u32 s28, s84, s37
	v_ashrrev_i32_e32 v3, 31, v2
	v_or_b32_e32 v14, 1, v2
	v_lshl_add_u64 v[24:25], s[38:39], 0, v[4:5]
	v_lshl_add_u64 v[26:27], s[38:39], 0, v[6:7]
	v_lshl_add_u64 v[28:29], s[38:39], 0, v[8:9]
	s_addc_u32 s29, s85, 0
	v_or_b32_e32 v16, 5, v2
	v_or_b32_e32 v18, 6, v2
	v_or_b32_e32 v20, 7, v2
	v_lshl_add_u64 v[2:3], s[38:39], 0, v[2:3]
	v_ashrrev_i32_e32 v15, 31, v14
	v_lshl_add_u64 v[22:23], s[38:39], 0, v[14:15]
	v_ashrrev_i32_e32 v17, 31, v16
	v_ashrrev_i32_e32 v19, 31, v18
	v_ashrrev_i32_e32 v21, 31, v20
	v_lshl_add_u64 v[16:17], s[38:39], 0, v[16:17]
	v_lshl_add_u64 v[18:19], s[38:39], 0, v[18:19]
	v_lshl_add_u64 v[20:21], s[38:39], 0, v[20:21]
	v_cmp_lt_i32_e32 vcc, 0, v36
	s_movk_i32 s3, 0x2000
	v_and_b32_e32 v58, 3, v12
	v_lshlrev_b32_e32 v53, 5, v58
	v_ashrrev_i32_e32 v55, 8, v52
	v_lshlrev_b32_e32 v50, 5, v55
	s_waitcnt vmcnt(6)
	v_add_f32_e32 v38, v13, v11
	s_waitcnt vmcnt(5)
	v_add_f32_e32 v39, v38, v30
	s_waitcnt vmcnt(4)
	v_add_f32_e32 v40, v39, v31
	s_waitcnt vmcnt(3)
	v_add_f32_e32 v41, v40, v32
	s_waitcnt vmcnt(2)
	v_add_f32_e32 v42, v41, v33
	s_waitcnt vmcnt(1)
	v_add_f32_e32 v43, v42, v34
	s_waitcnt vmcnt(0)
	v_add_f32_e32 v44, v43, v35
	ds_write_b32 v10, v44
	s_waitcnt lgkmcnt(0)
	s_barrier
	ds_read2st64_b32 v[10:11], v0 offset1:1
	ds_read2st64_b32 v[8:9], v0 offset0:2 offset1:3
	ds_read2st64_b32 v[6:7], v0 offset0:4 offset1:5
	ds_read2st64_b32 v[4:5], v0 offset0:6 offset1:7
	v_lshlrev_b32_e32 v0, 1, v51
	v_lshl_add_u64 v[30:31], s[28:29], 0, v[0:1]
	v_mad_u64_u32 v[32:33], s[28:29], v2, s64, v[30:31]
	v_mad_u64_u32 v[34:35], s[28:29], v22, s64, v[30:31]
	v_mad_i32_i24 v33, v3, s64, v33
	v_mad_i32_i24 v35, v23, s64, v35
	v_mov_b32_e32 v45, v88
	v_mov_b32_e32 v46, v89
	v_mov_b32_e32 v47, v90
	v_mov_b32_e32 v48, v91
	v_mad_u64_u32 v[2:3], s[28:29], v14, s92, v[0:1]
	v_mad_u64_u32 v[14:15], s[28:29], v24, s64, v[30:31]
	v_mad_i32_i24 v15, v25, s64, v15
	v_or_b32_e32 v37, v0, v37
	v_mov_b32_e32 v0, v92
	v_mov_b32_e32 v3, v93
	v_mad_u64_u32 v[22:23], s[28:29], v26, s64, v[30:31]
	v_mad_u64_u32 v[32:33], s[28:29], v28, s64, v[30:31]
	v_mad_u64_u32 v[24:25], s[28:29], v16, s64, v[30:31]
	v_mad_u64_u32 v[34:35], s[28:29], v18, s64, v[30:31]
	v_mad_u64_u32 v[30:31], s[28:29], v20, s64, v[30:31]
	v_mad_i32_i24 v23, v27, s64, v23
	v_mad_i32_i24 v33, v29, s64, v33
	v_mad_i32_i24 v25, v17, s64, v25
	v_mad_i32_i24 v35, v19, s64, v35
	v_mad_i32_i24 v31, v21, s64, v31
	v_mov_b32_e32 v14, v94
	v_mov_b32_e32 v15, v95
	v_mov_b32_e32 v16, v96
	v_mov_b32_e32 v17, v97
	v_mov_b32_e32 v18, v98
	v_mov_b32_e32 v19, v99
	v_mov_b32_e32 v20, v172
	v_mov_b32_e32 v21, v173
	v_mov_b32_e32 v22, v174
	v_mov_b32_e32 v23, v175
	s_waitcnt lgkmcnt(3)
	v_add_f32_e32 v10, 0, v10
	v_cndmask_b32_e32 v10, 0, v10, vcc
	v_add_f32_e32 v11, v11, v10
	v_cmp_lt_i32_e32 vcc, 1, v36
	s_waitcnt vmcnt(15)
	v_lshlrev_b32_e32 v25, 16, v45
	v_cndmask_b32_e32 v10, v10, v11, vcc
	s_waitcnt lgkmcnt(2)
	v_add_f32_e32 v8, v8, v10
	v_cmp_lt_i32_e32 vcc, 2, v36
	s_waitcnt vmcnt(14)
	v_lshlrev_b32_e32 v26, 16, v46
	s_waitcnt vmcnt(13)
	v_lshlrev_b32_e32 v27, 16, v47
	v_cndmask_b32_e32 v8, v10, v8, vcc
	v_add_f32_e32 v9, v9, v8
	v_cmp_lt_i32_e32 vcc, 3, v36
	v_mul_f32_e32 v25, 0x3e000000, v25
	s_waitcnt vmcnt(12)
	v_lshlrev_b32_e32 v28, 16, v48
	v_cndmask_b32_e32 v8, v8, v9, vcc
	s_waitcnt lgkmcnt(1)
	v_add_f32_e32 v6, v6, v8
	v_cmp_lt_i32_e32 vcc, 4, v36
	s_waitcnt vmcnt(11)
	v_lshlrev_b32_e32 v0, 16, v0
	v_mul_f32_e32 v0, 0x3e000000, v0
	v_cndmask_b32_e32 v6, v8, v6, vcc
	v_add_f32_e32 v7, v7, v6
	v_cmp_lt_i32_e32 vcc, 5, v36
	s_waitcnt vmcnt(10)
	v_lshlrev_b32_e32 v3, 16, v3
	v_cndmask_b32_e32 v6, v6, v7, vcc
	s_waitcnt lgkmcnt(0)
	v_add_f32_e32 v4, v4, v6
	v_cmp_lt_i32_e32 vcc, 6, v36
	s_nop 1
	v_cndmask_b32_e32 v4, v6, v4, vcc
	v_add_f32_e32 v5, v5, v4
	v_cmp_lt_i32_e32 vcc, 7, v36
	s_nop 1
	v_cndmask_b32_e32 v4, v4, v5, vcc
	v_add_f32_e32 v5, v13, v4
	v_add_f32_e32 v6, v38, v4
	v_mul_f32_e32 v13, 0x3fb8aa3b, v5
	v_mul_f32_e32 v5, 0xbfb8aa3b, v5
	v_mul_f32_e32 v24, 0x3fb8aa3b, v6
	v_exp_f32_e32 v5, v5
	v_mul_f32_e32 v6, 0xbfb8aa3b, v6
	v_exp_f32_e32 v13, v13
	v_exp_f32_e32 v24, v24
	v_exp_f32_e32 v6, v6
	v_mul_f32_e32 v5, v5, v26
	v_mul_f32_e32 v26, 0x3e000000, v27
	v_mul_f32_e32 v13, v25, v13
	v_cvt_pk_bf16_f32 v5, v5, s0
	v_mul_f32_e32 v24, v26, v24
	v_mul_f32_e32 v6, v6, v28
	v_cvt_pk_bf16_f32 v13, v13, s0
	ds_write_b16 v37, v5 offset:11264
	v_cvt_pk_bf16_f32 v5, v24, s0
	v_add_f32_e32 v7, v39, v4
	ds_write_b16 v37, v13 offset:2048
	ds_write_b16 v2, v5 offset:2048
	v_cvt_pk_bf16_f32 v5, v6, s0
	ds_write_b16 v2, v5 offset:11264
	v_mul_f32_e32 v5, 0x3fb8aa3b, v7
	v_exp_f32_e32 v5, v5
	v_mul_f32_e32 v6, 0xbfb8aa3b, v7
	v_exp_f32_e32 v6, v6
	v_add_f32_e32 v8, v40, v4
	v_mul_f32_e32 v0, v5, v0
	v_cvt_pk_bf16_f32 v0, v0, s0
	v_mul_f32_e32 v3, v6, v3
	ds_write_b16 v2, v0 offset:2192
	v_cvt_pk_bf16_f32 v0, v3, s0
	v_mul_f32_e32 v3, 0x3fb8aa3b, v8
	v_exp_f32_e32 v3, v3
	v_mul_f32_e32 v5, 0xbfb8aa3b, v8
	v_exp_f32_e32 v5, v5
	ds_write_b16 v2, v0 offset:11408
	s_waitcnt vmcnt(9)
	v_lshlrev_b32_e32 v0, 16, v14
	v_mul_f32_e32 v0, 0x3e000000, v0
	v_mul_f32_e32 v0, v3, v0
	s_waitcnt vmcnt(8)
	v_lshlrev_b32_e32 v3, 16, v15
	v_add_f32_e32 v9, v41, v4
	v_mul_f32_e32 v3, v5, v3
	v_cvt_pk_bf16_f32 v0, v0, s0
	ds_write_b16 v2, v0 offset:2336
	v_cvt_pk_bf16_f32 v0, v3, s0
	v_mul_f32_e32 v3, 0x3fb8aa3b, v9
	v_exp_f32_e32 v3, v3
	v_mul_f32_e32 v5, 0xbfb8aa3b, v9
	v_exp_f32_e32 v5, v5
	ds_write_b16 v2, v0 offset:11552
	s_waitcnt vmcnt(7)
	v_lshlrev_b32_e32 v0, 16, v16
	v_mul_f32_e32 v0, 0x3e000000, v0
	v_mul_f32_e32 v0, v3, v0
	s_waitcnt vmcnt(6)
	v_lshlrev_b32_e32 v3, 16, v17
	v_add_f32_e32 v10, v42, v4
	v_mul_f32_e32 v3, v5, v3
	v_cvt_pk_bf16_f32 v0, v0, s0
	ds_write_b16 v2, v0 offset:2480
	v_cvt_pk_bf16_f32 v0, v3, s0
	v_mul_f32_e32 v3, 0x3fb8aa3b, v10
	v_exp_f32_e32 v3, v3
	v_mul_f32_e32 v5, 0xbfb8aa3b, v10
	v_exp_f32_e32 v5, v5
	ds_write_b16 v2, v0 offset:11696
	s_waitcnt vmcnt(5)
	v_lshlrev_b32_e32 v0, 16, v18
	v_mul_f32_e32 v0, 0x3e000000, v0
	v_mul_f32_e32 v0, v3, v0
	s_waitcnt vmcnt(4)
	v_lshlrev_b32_e32 v3, 16, v19
	v_add_f32_e32 v11, v43, v4
	v_mul_f32_e32 v3, v5, v3
	v_cvt_pk_bf16_f32 v0, v0, s0
	ds_write_b16 v2, v0 offset:2624
	v_cvt_pk_bf16_f32 v0, v3, s0
	v_mul_f32_e32 v3, 0x3fb8aa3b, v11
	v_exp_f32_e32 v3, v3
	v_mul_f32_e32 v5, 0xbfb8aa3b, v11
	v_exp_f32_e32 v5, v5
	ds_write_b16 v2, v0 offset:11840
	s_waitcnt vmcnt(3)
	v_lshlrev_b32_e32 v0, 16, v20
	v_mul_f32_e32 v0, 0x3e000000, v0
	v_mul_f32_e32 v0, v3, v0
	s_waitcnt vmcnt(2)
	v_lshlrev_b32_e32 v3, 16, v21
	v_add_f32_e32 v4, v44, v4
	v_mul_f32_e32 v3, v5, v3
	v_cvt_pk_bf16_f32 v0, v0, s0
	ds_write_b16 v2, v0 offset:2768
	v_cvt_pk_bf16_f32 v0, v3, s0
	v_mul_f32_e32 v3, 0x3fb8aa3b, v4
	v_exp_f32_e32 v3, v3
	v_mul_f32_e32 v4, 0xbfb8aa3b, v4
	v_exp_f32_e32 v4, v4
	ds_write_b16 v2, v0 offset:11984
	s_waitcnt vmcnt(1)
	v_lshlrev_b32_e32 v0, 16, v22
	v_mul_f32_e32 v0, 0x3e000000, v0
	v_mul_f32_e32 v0, v3, v0
	s_waitcnt vmcnt(0)
	v_lshlrev_b32_e32 v3, 16, v23
	v_mul_f32_e32 v3, v4, v3
	v_cvt_pk_bf16_f32 v0, v0, s0
	ds_write_b16 v2, v0 offset:2912
	v_cvt_pk_bf16_f32 v0, v3, s0
	ds_write_b16 v2, v0 offset:12128
	v_mov_b32_e32 v0, v180
	v_mov_b64_e32 v[4:5], s[84:85]
	v_ashrrev_i32_e32 v30, 7, v0
	v_lshlrev_b32_e32 v2, 4, v30
	v_ashrrev_i32_e32 v3, 31, v2
	v_lshl_add_u64 v[2:3], s[38:39], 0, v[2:3]
	v_mad_u64_u32 v[4:5], s[28:29], v2, s64, v[4:5]
	v_and_b32_e32 v13, 0x7f, v0
	v_mad_i32_i24 v5, v3, s64, v5
	v_lshl_add_u64 v[2:3], v[4:5], 0, s[94:95]
	v_lshlrev_b32_e32 v0, 1, v13
	v_lshl_add_u64 v[2:3], v[2:3], 0, v[0:1]
	v_add_co_u32_e32 v4, vcc, s31, v2
	v_ashrrev_i32_e32 v39, 2, v52
	s_nop 0
	v_addc_co_u32_e32 v5, vcc, 0, v3, vcc
	v_add_co_u32_e32 v6, vcc, s3, v2
	s_movk_i32 s3, 0x4000
	s_nop 0
	v_addc_co_u32_e32 v7, vcc, 0, v3, vcc
	v_add_co_u32_e32 v8, vcc, s3, v2
	s_movk_i32 s3, 0x5000
	s_nop 0
	v_addc_co_u32_e32 v9, vcc, 0, v3, vcc
	v_add_co_u32_e32 v10, vcc, s3, v2
	s_movk_i32 s3, 0x6000
	s_nop 0
	v_addc_co_u32_e32 v11, vcc, 0, v3, vcc
	v_add_co_u32_e32 v14, vcc, s3, v2
	s_movk_i32 s3, 0x7000
	s_nop 0
	v_addc_co_u32_e32 v15, vcc, 0, v3, vcc
	v_add_co_u32_e32 v16, vcc, s3, v2
	s_mov_b32 s3, 0x9000
	s_nop 0
	v_addc_co_u32_e32 v17, vcc, 0, v3, vcc
	v_add_co_u32_e32 v18, vcc, s3, v2
	s_mov_b32 s3, 0xa000
	s_nop 0
	v_addc_co_u32_e32 v19, vcc, 0, v3, vcc
	v_mov_b32_e32 v22, v176
	v_mov_b32_e32 v23, v177
	v_mov_b32_e32 v24, v178
	v_mov_b32_e32 v25, v179
	v_mov_b32_e32 v26, v195
	v_mov_b32_e32 v27, v196
	v_mov_b32_e32 v28, v197
	v_mov_b32_e32 v29, v198
	v_add_co_u32_e32 v4, vcc, s3, v2
	s_mov_b32 s3, 0xb000
	s_nop 0
	v_addc_co_u32_e32 v5, vcc, 0, v3, vcc
	v_add_co_u32_e32 v6, vcc, s3, v2
	s_mov_b32 s3, 0xc000
	s_nop 0
	v_addc_co_u32_e32 v7, vcc, 0, v3, vcc
	v_add_co_u32_e32 v8, vcc, s3, v2
	s_mov_b32 s3, 0xe000
	s_nop 0
	v_addc_co_u32_e32 v9, vcc, 0, v3, vcc
	v_add_co_u32_e32 v10, vcc, s3, v2
	s_mov_b32 s3, 0xf000
	s_nop 0
	v_addc_co_u32_e32 v11, vcc, 0, v3, vcc
	v_add_co_u32_e32 v14, vcc, s3, v2
	s_mov_b32 s3, 0x10000
	s_nop 0
	v_addc_co_u32_e32 v15, vcc, 0, v3, vcc
	v_add_co_u32_e32 v16, vcc, s3, v2
	s_mov_b32 s3, 0x11000
	s_nop 0
	v_addc_co_u32_e32 v17, vcc, 0, v3, vcc
	v_add_co_u32_e32 v18, vcc, s3, v2
	s_mov_b32 s3, 0x13000
	s_nop 0
	v_addc_co_u32_e32 v19, vcc, 0, v3, vcc
	v_add_co_u32_e32 v2, vcc, s3, v2
	s_ashr_i32 s3, s2, 31
	s_lshl_b64 s[28:29], s[2:3], 15
	v_addc_co_u32_e32 v3, vcc, 0, v3, vcc
	v_mov_b32_e32 v31, v199
	v_mov_b32_e32 v32, v200
	v_mov_b32_e32 v33, v201
	v_mov_b32_e32 v34, v202
	v_mov_b32_e32 v35, v203
	v_mov_b32_e32 v36, v204
	v_mov_b32_e32 v37, v205
	v_mov_b32_e32 v38, v206
	s_add_u32 s28, s82, s28
	v_lshlrev_b32_e32 v2, 6, v39
	v_and_b32_e32 v40, 3, v52
	s_addc_u32 s29, s83, s29
	v_ashrrev_i32_e32 v3, 31, v2
	v_lshl_add_u64 v[2:3], v[2:3], 2, s[28:29]
	v_lshlrev_b32_e32 v0, 6, v40
	v_lshl_add_u64 v[10:11], v[2:3], 0, v[0:1]
	v_mov_b32_e32 v2, v66
	v_mov_b32_e32 v3, v67
	v_mov_b32_e32 v4, v68
	v_mov_b32_e32 v5, v69
	v_mov_b32_e32 v6, v70
	v_mov_b32_e32 v7, v71
	v_mov_b32_e32 v8, v72
	v_mov_b32_e32 v9, v73
	v_mov_b32_e32 v14, v74
	v_mov_b32_e32 v15, v75
	v_mov_b32_e32 v16, v76
	v_mov_b32_e32 v17, v77
	v_mov_b32_e32 v18, v78
	v_mov_b32_e32 v19, v79
	v_mov_b32_e32 v20, v80
	v_mov_b32_e32 v21, v81
	v_lshlrev_b32_e32 v10, 5, v30
	v_mad_u32_u24 v10, v13, s92, v10
	v_and_b32_e32 v0, 31, v52
	v_or_b32_e32 v56, v50, v0
	v_mul_lo_u32 v57, v56, s92
	v_cmp_lt_i32_e32 vcc, -1, v55
	s_waitcnt vmcnt(18)
	v_lshl_or_b32 v22, v23, 16, v22
	s_waitcnt vmcnt(16)
	v_lshl_or_b32 v23, v25, 16, v24
	s_waitcnt vmcnt(14)
	v_lshl_or_b32 v24, v27, 16, v26
	s_waitcnt vmcnt(12)
	v_lshl_or_b32 v25, v29, 16, v28
	s_waitcnt vmcnt(10)
	v_lshl_or_b32 v26, v32, 16, v31
	s_waitcnt vmcnt(8)
	v_lshl_or_b32 v27, v34, 16, v33
	s_waitcnt vmcnt(6)
	v_lshl_or_b32 v28, v36, 16, v35
	s_waitcnt vmcnt(4)
	v_lshl_or_b32 v29, v38, 16, v37
	ds_write_b128 v10, v[22:25] offset:20480
	ds_write_b128 v10, v[26:29] offset:20496
	v_bfe_u32 v26, v52, 5, 1
	v_lshlrev_b32_e32 v27, 4, v26
	v_or_b32_e32 v28, v53, v0
	v_mad_u32_u24 v22, v28, s92, v27
	s_waitcnt vmcnt(3)
	v_cvt_pk_bf16_f32 v2, v2, v3
	v_cvt_pk_bf16_f32 v3, v4, v5
	s_waitcnt vmcnt(2)
	v_cvt_pk_bf16_f32 v4, v6, v7
	v_mul_lo_u32 v6, v39, s92
	v_cvt_pk_bf16_f32 v5, v8, v9
	v_lshl_add_u32 v6, v40, 5, v6
	ds_write_b128 v6, v[2:5] offset:38912
	s_waitcnt vmcnt(1)
	v_cvt_pk_bf16_f32 v2, v14, v15
	v_cvt_pk_bf16_f32 v3, v16, v17
	s_waitcnt vmcnt(0)
	v_cvt_pk_bf16_f32 v4, v18, v19
	v_cvt_pk_bf16_f32 v5, v20, v21
	ds_write_b128 v6, v[2:5] offset:38928
	s_waitcnt lgkmcnt(0)
	s_barrier
	ds_read_b128 v[2:5], v22 offset:38912
	v_add_u32_e32 v23, v57, v27
	ds_read_b128 v[42:45], v23 offset:2048
	ds_read_b128 v[38:41], v23 offset:2080
	ds_read_b128 v[18:21], v22 offset:38944
	s_waitcnt lgkmcnt(2)
	v_mfma_f32_32x32x16_bf16 v[2:17], v[2:5], v[42:45], 0
	v_mul_u32_u24_e32 v59, 0x90, v28
	v_lshlrev_b32_e32 v54, 2, v26
	v_lshlrev_b32_e32 v60, 3, v26
	v_mad_u32_u24 v61, v0, s92, v27
	s_waitcnt lgkmcnt(0)
	v_mfma_f32_32x32x16_bf16 v[2:17], v[18:21], v[38:41], v[2:17]
	ds_read_b128 v[18:21], v22 offset:38976
	ds_read_b128 v[46:49], v23 offset:2112
	ds_read_b128 v[34:37], v23 offset:2144
	ds_read_b128 v[22:25], v22 offset:39008
	s_waitcnt lgkmcnt(2)
	v_mfma_f32_32x32x16_bf16 v[2:17], v[18:21], v[46:49], v[2:17]
	s_waitcnt lgkmcnt(0)
	v_mfma_f32_32x32x16_bf16 v[2:17], v[22:25], v[34:37], v[2:17]
	s_and_saveexec_b64 s[28:29], vcc
	s_cbranch_execz .LBB0_94
	ds_read_b128 v[18:21], v61 offset:11264
	ds_read_b128 v[62:65], v61 offset:11296
	s_movk_i32 s3, 0x100
	v_cmp_gt_u32_e32 vcc, s3, v52
	s_waitcnt lgkmcnt(1)
	v_mfma_f32_32x32x16_bf16 v[18:33], v[18:21], v[42:45], 0
	s_waitcnt lgkmcnt(0)
	v_mfma_f32_32x32x16_bf16 v[18:33], v[62:65], v[38:41], v[18:33]
	ds_read_b128 v[62:65], v61 offset:11328
	s_waitcnt lgkmcnt(0)
	v_mfma_f32_32x32x16_bf16 v[18:33], v[62:65], v[46:49], v[18:33]
	ds_read_b128 v[62:65], v61 offset:11360
	s_waitcnt lgkmcnt(0)
	v_mfma_f32_32x32x16_bf16 v[18:33], v[62:65], v[34:37], v[18:33]
	s_and_saveexec_b64 s[40:41], vcc
	s_cbranch_execz .LBB0_93
	v_cmp_lt_u32_e32 vcc, v54, v0
	v_or_b32_e32 v52, 2, v54
	s_nop 7
	v_cndmask_b32_e32 v19, 0, v19, vcc
	v_cmp_le_u32_e32 vcc, v54, v0
	s_nop 1
	v_cndmask_b32_e32 v18, 0, v18, vcc
	v_cmp_le_u32_e32 vcc, v52, v0
	v_or_b32_e32 v52, 3, v54
	s_nop 0
	v_cndmask_b32_e32 v20, 0, v20, vcc
	v_cmp_le_u32_e32 vcc, v52, v0
	v_or_b32_e32 v52, 8, v54
	s_nop 0
	v_cndmask_b32_e32 v21, 0, v21, vcc
	v_cmp_le_u32_e32 vcc, v52, v0
	v_or_b32_e32 v52, 9, v54
	s_nop 0
	v_cndmask_b32_e32 v22, 0, v22, vcc
	v_cmp_le_u32_e32 vcc, v52, v0
	v_or_b32_e32 v52, 10, v54
	s_nop 0
	v_cndmask_b32_e32 v23, 0, v23, vcc
	v_cmp_le_u32_e32 vcc, v52, v0
	v_or_b32_e32 v52, 11, v54
	s_nop 0
	v_cndmask_b32_e32 v24, 0, v24, vcc
	v_cmp_le_u32_e32 vcc, v52, v0
	v_or_b32_e32 v52, 16, v54
	s_nop 0
	v_cndmask_b32_e32 v25, 0, v25, vcc
	v_cmp_le_u32_e32 vcc, v52, v0
	v_or_b32_e32 v52, 17, v54
	s_nop 0
	v_cndmask_b32_e32 v26, 0, v26, vcc
	v_cmp_le_u32_e32 vcc, v52, v0
	v_or_b32_e32 v52, 18, v54
	s_nop 0
	v_cndmask_b32_e32 v27, 0, v27, vcc
	v_cmp_le_u32_e32 vcc, v52, v0
	v_or_b32_e32 v52, 19, v54
	s_nop 0
	v_cndmask_b32_e32 v28, 0, v28, vcc
	v_cmp_le_u32_e32 vcc, v52, v0
	v_or_b32_e32 v52, 24, v54
	s_nop 0
	v_cndmask_b32_e32 v29, 0, v29, vcc
	v_cmp_le_u32_e32 vcc, v52, v0
	v_or_b32_e32 v52, 25, v54
	s_nop 0
	v_cndmask_b32_e32 v30, 0, v30, vcc
	v_cmp_le_u32_e32 vcc, v52, v0
	v_or_b32_e32 v52, 26, v54
	s_nop 0
	v_cndmask_b32_e32 v31, 0, v31, vcc
	v_cmp_le_u32_e32 vcc, v52, v0
	v_or_b32_e32 v52, 27, v54
	s_nop 0
	v_cndmask_b32_e32 v32, 0, v32, vcc
	v_cmp_le_u32_e32 vcc, v52, v0
	s_nop 1
	v_cndmask_b32_e32 v33, 0, v33, vcc

	.amdhsa_kernel _Z14fwd_megakernel6Paramsiii
		.amdhsa_group_segment_fixed_size 135168
		.amdhsa_private_segment_fixed_size 0
		.amdhsa_kernarg_size 496
		.amdhsa_user_sgpr_count 2
		.amdhsa_user_sgpr_dispatch_ptr 0
		.amdhsa_user_sgpr_queue_ptr 0
		.amdhsa_user_sgpr_kernarg_segment_ptr 1
		.amdhsa_user_sgpr_dispatch_id 0
		.amdhsa_user_sgpr_kernarg_preload_length 0
		.amdhsa_user_sgpr_kernarg_preload_offset 0
		.amdhsa_user_sgpr_private_segment_size 0
		.amdhsa_uses_dynamic_stack 0
		.amdhsa_enable_private_segment 0
		.amdhsa_system_sgpr_workgroup_id_x 1
		.amdhsa_system_sgpr_workgroup_id_y 0
		.amdhsa_system_sgpr_workgroup_id_z 0
		.amdhsa_system_sgpr_workgroup_info 0
		.amdhsa_system_vgpr_workitem_id 2
		.amdhsa_next_free_vgpr 256
		.amdhsa_next_free_sgpr 102
		.amdhsa_accum_offset 256
		.amdhsa_reserve_vcc 1
		.amdhsa_float_round_mode_32 0
		.amdhsa_float_round_mode_16_64 0
		.amdhsa_float_denorm_mode_32 3
		.amdhsa_float_denorm_mode_16_64 3
		.amdhsa_dx10_clamp 1
		.amdhsa_ieee_mode 1
		.amdhsa_fp16_overflow 0
		.amdhsa_tg_split 0
		.amdhsa_exception_fp_ieee_invalid_op 0
		.amdhsa_exception_fp_denorm_src 0
		.amdhsa_exception_fp_ieee_div_zero 0
		.amdhsa_exception_fp_ieee_overflow 0
		.amdhsa_exception_fp_ieee_underflow 0
		.amdhsa_exception_fp_ieee_inexact 0
		.amdhsa_exception_int_div_zero 0
	.end_amdhsa_kernel

amdhsa.kernels:
  - .agpr_count:     0
    .args:
      - .offset:         0
        .size:           224
        .value_kind:     by_value
      - .offset:         224
        .size:           4
        .value_kind:     by_value
      - .offset:         228
        .size:           4
        .value_kind:     by_value
      - .offset:         232
        .size:           4
        .value_kind:     by_value
      - .offset:         240
        .size:           4
        .value_kind:     hidden_block_count_x
      - .offset:         244
        .size:           4
        .value_kind:     hidden_block_count_y
      - .offset:         248
        .size:           4
        .value_kind:     hidden_block_count_z
      - .offset:         252
        .size:           2
        .value_kind:     hidden_group_size_x
      - .offset:         254
        .size:           2
        .value_kind:     hidden_group_size_y
      - .offset:         256
        .size:           2
        .value_kind:     hidden_group_size_z
      - .offset:         258
        .size:           2
        .value_kind:     hidden_remainder_x
      - .offset:         260
        .size:           2
        .value_kind:     hidden_remainder_y
      - .offset:         262
        .size:           2
        .value_kind:     hidden_remainder_z
      - .offset:         280
        .size:           8
        .value_kind:     hidden_global_offset_x
      - .offset:         288
        .size:           8
        .value_kind:     hidden_global_offset_y
      - .offset:         296
        .size:           8
        .value_kind:     hidden_global_offset_z
      - .offset:         304
        .size:           2
        .value_kind:     hidden_grid_dims
      - .offset:         328
        .size:           8
        .value_kind:     hidden_multigrid_sync_arg
    .group_segment_fixed_size: 135168
    .kernarg_segment_align: 8
    .kernarg_segment_size: 496
    .language:       OpenCL C
    .language_version:
      - 2
      - 0
    .max_flat_workgroup_size: 512
    .name:           _Z14fwd_megakernel6Paramsiii
    .private_segment_fixed_size: 0
    .sgpr_count:     108
    .sgpr_spill_count: 423
    .symbol:         _Z14fwd_megakernel6Paramsiii.kd
    .uniform_work_group_size: 1
    .uses_dynamic_stack: false
    .vgpr_count:     256
    .vgpr_spill_count: 0
    .wavefront_size: 64
